# q_tile GEMM: next tile's global loads issued right after the LDS stores of the current tile (a full iteration of latency cover under the half-stagger)
# baseline (speedup 1.0000x reference)
; #define MFMA(a, b, c) __builtin_amdgcn_mfma_f32_32x32x16_bf16((a), (b), (c), 0, 0, 0)
; template <int BM, int BN, int BK, int WAVES_M, int WAVES_N, int UNSWAP_FROM>
; DI void gemm_mainloop(const int tid, const bf16_t* __restrict__ A, int lda, const bf16_t* __restrict__ Bt, int ldb, int K, unsigned char* smem,
;                       f32x16 (&acc)[BM / WAVES_M / 32][BN / WAVES_N / 32]) {
;     ...
;     for (int kt = 0; kt < nk; ++kt) {
;         const int buf = kt & 1;
;         if (kt + 1 < nk) G_LOAD(kt + 1);
;         const unsigned char* sa_ = smem + buf * STAGE; const unsigned char* sb_ = sa_ + A_ST;
; #pragma unroll
;         for (int ks = 0; ks < BK / 16; ++ks) {
;             bf16x8 af[WM], bfr[WN];
; #pragma unroll
;             for (int i = 0; i < WM; ++i) af[i] = *(const bf16x8*)(sa_ + (((wm * WM + i) * 32 + r) * LS + ks * 16 + h * 8) * 2);
; #pragma unroll
;             for (int j = 0; j < WN; ++j) bfr[j] = *(const bf16x8*)(sb_ + (((wn * WN + j) * 32 + r) * LS + ks * 16 + h * 8) * 2);
; #pragma unroll
;             for (int i = 0; i < WM; ++i)
; #pragma unroll
;                 for (int j = 0; j < WN; ++j) {
;                     if (j < UNSWAP_FROM) acc[i][j] = MFMA(bfr[j], af[i], acc[i][j]);
;                     else acc[i][j] = MFMA(af[i], bfr[j], acc[i][j]);
;                 }
;         }
;         if (kt + 1 < nk) G_STORE(buf ^ 1);
;         __syncthreads();
.Lq_stg_beg:
	global_load_dwordx4 v[96:99], v[120:121], off offset:64
	global_load_dwordx4 v[100:103], v[122:123], off offset:64
	global_load_dwordx4 v[104:107], v[124:125], off offset:64
	global_load_dwordx4 v[108:111], v[126:127], off offset:64
	global_load_dwordx4 v[112:115], v[128:129], off offset:64
	v_lshrrev_b32_e32 v0, 1, v116
	v_and_or_b32 v1, v0, s44, v119
	v_and_b32_e32 v0, 16, v0
	v_mul_u32_u24_e32 v2, 0x50, v119
	v_mul_lo_u32 v1, v1, s5
	v_add3_u32 v133, v0, v2, s10
	v_add3_u32 v134, v1, v0, s10
	ds_read_b128 v[0:3], v133 offset:12800
	ds_read_b128 v[4:7], v133 offset:15360
	ds_read_b128 v[8:11], v133 offset:17920
	ds_read_b128 v[12:15], v133 offset:20480
	ds_read_b128 v[16:19], v133 offset:23040
	ds_read_b128 v[20:23], v134
	ds_read_b128 v[136:139], v134 offset:32
	ds_read_b128 v[24:27], v133 offset:10240
	ds_read_b128 v[140:143], v133 offset:10272
	ds_read_b128 v[144:147], v133 offset:12832
	ds_read_b128 v[148:151], v133 offset:15392
	ds_read_b128 v[152:155], v133 offset:17952
	ds_read_b128 v[156:159], v133 offset:20512
	ds_read_b128 v[160:163], v133 offset:23072
	s_waitcnt lgkmcnt(6)
	v_mfma_f32_32x32x16_bf16 v[80:95], v[24:27], v[20:23], 0
	s_barrier
	s_waitcnt vmcnt(4)
	ds_write_b128 v130, v[96:99] offset:25600
	s_waitcnt vmcnt(3)
	ds_write_b128 v131, v[100:103] offset:25600
	s_waitcnt vmcnt(2)
	ds_write_b128 v130, v[104:107] offset:35840
	s_waitcnt vmcnt(1)
	ds_write_b128 v131, v[108:111] offset:35840
	s_waitcnt vmcnt(0)
	ds_write_b128 v132, v[112:115] offset:35840
	global_load_dwordx4 v[96:99], v[120:121], off offset:128
	global_load_dwordx4 v[100:103], v[122:123], off offset:128
	global_load_dwordx4 v[104:107], v[124:125], off offset:128
	global_load_dwordx4 v[108:111], v[126:127], off offset:128
	global_load_dwordx4 v[112:115], v[128:129], off offset:128
	s_waitcnt lgkmcnt(0)
	s_barrier
	v_mfma_f32_32x32x16_bf16 v[64:79], v[0:3], v[20:23], 0
	v_mfma_f32_32x32x16_bf16 v[48:63], v[4:7], v[20:23], 0
	v_mfma_f32_32x32x16_bf16 v[32:47], v[8:11], v[20:23], 0
	v_mfma_f32_32x32x16_bf16 v[0:15], v[12:15], v[20:23], 0
	v_mfma_f32_32x32x16_bf16 v[16:31], v[16:19], v[20:23], 0
	v_mfma_f32_32x32x16_bf16 v[64:79], v[144:147], v[136:139], v[64:79]
	v_mfma_f32_32x32x16_bf16 v[48:63], v[148:151], v[136:139], v[48:63]
	v_mfma_f32_32x32x16_bf16 v[32:47], v[152:155], v[136:139], v[32:47]
	v_mfma_f32_32x32x16_bf16 v[0:15], v[156:159], v[136:139], v[0:15]
	v_mfma_f32_32x32x16_bf16 v[16:31], v[160:163], v[136:139], v[16:31]
	v_mfma_f32_32x32x16_bf16 v[80:95], v[140:143], v[136:139], v[80:95]
	ds_read_b128 v[136:139], v133 offset:38400
	ds_read_b128 v[140:143], v133 offset:40960
	ds_read_b128 v[144:147], v133 offset:43520
	ds_read_b128 v[148:151], v133 offset:46080
	ds_read_b128 v[152:155], v133 offset:48640
	ds_read_b128 v[156:159], v134 offset:25600
	ds_read_b128 v[160:163], v134 offset:25632
	ds_read_b128 v[164:167], v133 offset:35840
	ds_read_b128 v[168:171], v133 offset:35872
	s_waitcnt lgkmcnt(3)
	v_mfma_f32_32x32x16_bf16 v[64:79], v[136:139], v[156:159], v[64:79]
	v_mfma_f32_32x32x16_bf16 v[48:63], v[140:143], v[156:159], v[48:63]
	v_mfma_f32_32x32x16_bf16 v[32:47], v[144:147], v[156:159], v[32:47]
	v_mfma_f32_32x32x16_bf16 v[0:15], v[148:151], v[156:159], v[0:15]
	v_mfma_f32_32x32x16_bf16 v[16:31], v[152:155], v[156:159], v[16:31]
	ds_read_b128 v[136:139], v133 offset:38432
	ds_read_b128 v[140:143], v133 offset:40992
	ds_read_b128 v[144:147], v133 offset:43552
	ds_read_b128 v[148:151], v133 offset:46112
	ds_read_b128 v[152:155], v133 offset:48672
	s_barrier
	s_waitcnt vmcnt(4)
	ds_write_b128 v130, v[96:99]
	s_waitcnt vmcnt(3)
	ds_write_b128 v131, v[100:103]
	s_waitcnt vmcnt(2)
	ds_write_b128 v130, v[104:107] offset:10240
	s_waitcnt vmcnt(1)
	ds_write_b128 v131, v[108:111] offset:10240
	s_waitcnt vmcnt(0)
	ds_write_b128 v132, v[112:115] offset:10240
	global_load_dwordx4 v[96:99], v[120:121], off offset:192
	global_load_dwordx4 v[100:103], v[122:123], off offset:192
	global_load_dwordx4 v[104:107], v[124:125], off offset:192
	global_load_dwordx4 v[108:111], v[126:127], off offset:192
	global_load_dwordx4 v[112:115], v[128:129], off offset:192
	s_waitcnt lgkmcnt(0)
	s_barrier
	s_mov_b64 s[100:101], 0x80
	s_movk_i32 s99, 6
.Lq_roll:
	v_mfma_f32_32x32x16_bf16 v[80:95], v[164:167], v[156:159], v[80:95]
	v_mfma_f32_32x32x16_bf16 v[64:79], v[136:139], v[160:163], v[64:79]
	v_mfma_f32_32x32x16_bf16 v[48:63], v[140:143], v[160:163], v[48:63]
	v_mfma_f32_32x32x16_bf16 v[32:47], v[144:147], v[160:163], v[32:47]
	v_mfma_f32_32x32x16_bf16 v[0:15], v[148:151], v[160:163], v[0:15]
	v_mfma_f32_32x32x16_bf16 v[16:31], v[152:155], v[160:163], v[16:31]
	v_mfma_f32_32x32x16_bf16 v[80:95], v[168:171], v[160:163], v[80:95]
	ds_read_b128 v[136:139], v133 offset:12800
	ds_read_b128 v[140:143], v133 offset:15360
	ds_read_b128 v[144:147], v133 offset:17920
	ds_read_b128 v[148:151], v133 offset:20480
	ds_read_b128 v[152:155], v133 offset:23040
	ds_read_b128 v[156:159], v134
	ds_read_b128 v[160:163], v134 offset:32
	ds_read_b128 v[164:167], v133 offset:10240
	ds_read_b128 v[168:171], v133 offset:10272
	s_waitcnt lgkmcnt(3)
	v_mfma_f32_32x32x16_bf16 v[64:79], v[136:139], v[156:159], v[64:79]
	v_mfma_f32_32x32x16_bf16 v[48:63], v[140:143], v[156:159], v[48:63]
	v_mfma_f32_32x32x16_bf16 v[32:47], v[144:147], v[156:159], v[32:47]
	v_mfma_f32_32x32x16_bf16 v[0:15], v[148:151], v[156:159], v[0:15]
	v_mfma_f32_32x32x16_bf16 v[16:31], v[152:155], v[156:159], v[16:31]
	ds_read_b128 v[136:139], v133 offset:12832
	ds_read_b128 v[140:143], v133 offset:15392
	ds_read_b128 v[144:147], v133 offset:17952
	ds_read_b128 v[148:151], v133 offset:20512
	ds_read_b128 v[152:155], v133 offset:23072
	s_barrier
; #define MFMA(a, b, c) __builtin_amdgcn_mfma_f32_32x32x16_bf16((a), (b), (c), 0, 0, 0)
; template <int BM, int BN, int BK, int WAVES_M, int WAVES_N, int UNSWAP_FROM>
; DI void gemm_mainloop(const int tid, const bf16_t* __restrict__ A, int lda, const bf16_t* __restrict__ Bt, int ldb, int K, unsigned char* smem,
;                       f32x16 (&acc)[BM / WAVES_M / 32][BN / WAVES_N / 32]) {
;     ...
;     for (int kt = 0; kt < nk; ++kt) {
;         const int buf = kt & 1;
;         if (kt + 1 < nk) G_LOAD(kt + 1);
;         const unsigned char* sa_ = smem + buf * STAGE; const unsigned char* sb_ = sa_ + A_ST;
; #pragma unroll
;         for (int ks = 0; ks < BK / 16; ++ks) {
;             bf16x8 af[WM], bfr[WN];
; #pragma unroll
;             for (int i = 0; i < WM; ++i) af[i] = *(const bf16x8*)(sa_ + (((wm * WM + i) * 32 + r) * LS + ks * 16 + h * 8) * 2);
; #pragma unroll
;             for (int j = 0; j < WN; ++j) bfr[j] = *(const bf16x8*)(sb_ + (((wn * WN + j) * 32 + r) * LS + ks * 16 + h * 8) * 2);
; #pragma unroll
;             for (int i = 0; i < WM; ++i)
; #pragma unroll
;                 for (int j = 0; j < WN; ++j) {
;                     if (j < UNSWAP_FROM) acc[i][j] = MFMA(bfr[j], af[i], acc[i][j]);
;                     else acc[i][j] = MFMA(af[i], bfr[j], acc[i][j]);
;                 }
;         }
;         if (kt + 1 < nk) G_STORE(buf ^ 1);
;         __syncthreads();
	s_waitcnt vmcnt(4)
	ds_write_b128 v130, v[96:99] offset:25600
	s_waitcnt vmcnt(3)
	ds_write_b128 v131, v[100:103] offset:25600
	s_waitcnt vmcnt(2)
	ds_write_b128 v130, v[104:107] offset:35840
	s_waitcnt vmcnt(1)
	ds_write_b128 v131, v[108:111] offset:35840
	s_waitcnt vmcnt(0)
	ds_write_b128 v132, v[112:115] offset:35840
	global_load_dwordx4 v[96:99], v[120:121], off offset:256
	global_load_dwordx4 v[100:103], v[122:123], off offset:256
	global_load_dwordx4 v[104:107], v[124:125], off offset:256
	global_load_dwordx4 v[108:111], v[126:127], off offset:256
	global_load_dwordx4 v[112:115], v[128:129], off offset:256
	s_waitcnt lgkmcnt(0)
	s_barrier
	v_mfma_f32_32x32x16_bf16 v[80:95], v[164:167], v[156:159], v[80:95]
	v_mfma_f32_32x32x16_bf16 v[64:79], v[136:139], v[160:163], v[64:79]
	v_mfma_f32_32x32x16_bf16 v[48:63], v[140:143], v[160:163], v[48:63]
	v_mfma_f32_32x32x16_bf16 v[32:47], v[144:147], v[160:163], v[32:47]
	v_mfma_f32_32x32x16_bf16 v[0:15], v[148:151], v[160:163], v[0:15]
	v_mfma_f32_32x32x16_bf16 v[16:31], v[152:155], v[160:163], v[16:31]
	v_mfma_f32_32x32x16_bf16 v[80:95], v[168:171], v[160:163], v[80:95]
	ds_read_b128 v[136:139], v133 offset:38400
	ds_read_b128 v[140:143], v133 offset:40960
	ds_read_b128 v[144:147], v133 offset:43520
	ds_read_b128 v[148:151], v133 offset:46080
	ds_read_b128 v[152:155], v133 offset:48640
	ds_read_b128 v[156:159], v134 offset:25600
	ds_read_b128 v[160:163], v134 offset:25632
	ds_read_b128 v[164:167], v133 offset:35840
	ds_read_b128 v[168:171], v133 offset:35872
	s_waitcnt lgkmcnt(3)
	v_mfma_f32_32x32x16_bf16 v[64:79], v[136:139], v[156:159], v[64:79]
	v_mfma_f32_32x32x16_bf16 v[48:63], v[140:143], v[156:159], v[48:63]
	v_mfma_f32_32x32x16_bf16 v[32:47], v[144:147], v[156:159], v[32:47]
	v_mfma_f32_32x32x16_bf16 v[0:15], v[148:151], v[156:159], v[0:15]
	v_mfma_f32_32x32x16_bf16 v[16:31], v[152:155], v[156:159], v[16:31]
	ds_read_b128 v[136:139], v133 offset:38432
	ds_read_b128 v[140:143], v133 offset:40992
	ds_read_b128 v[144:147], v133 offset:43552
	ds_read_b128 v[148:151], v133 offset:46112
	ds_read_b128 v[152:155], v133 offset:48672
	s_barrier
	s_waitcnt vmcnt(4)
	ds_write_b128 v130, v[96:99]
	s_waitcnt vmcnt(3)
	ds_write_b128 v131, v[100:103]
	s_waitcnt vmcnt(2)
	ds_write_b128 v130, v[104:107] offset:10240
	s_waitcnt vmcnt(1)
	ds_write_b128 v131, v[108:111] offset:10240
	s_waitcnt vmcnt(0)
	ds_write_b128 v132, v[112:115] offset:10240
	s_waitcnt lgkmcnt(0)
	v_lshl_add_u64 v[120:121], v[120:121], 0, s[100:101]
	v_lshl_add_u64 v[122:123], v[122:123], 0, s[100:101]
	v_lshl_add_u64 v[124:125], v[124:125], 0, s[100:101]
	v_lshl_add_u64 v[126:127], v[126:127], 0, s[100:101]
	v_lshl_add_u64 v[128:129], v[128:129], 0, s[100:101]
	global_load_dwordx4 v[96:99], v[120:121], off offset:192
	global_load_dwordx4 v[100:103], v[122:123], off offset:192
	global_load_dwordx4 v[104:107], v[124:125], off offset:192
	global_load_dwordx4 v[108:111], v[126:127], off offset:192
	global_load_dwordx4 v[112:115], v[128:129], off offset:192
	s_barrier
	s_add_i32 s99, s99, -1
	s_cmp_lg_u32 s99, 0
	s_cbranch_scc1 .Lq_roll
	s_mov_b32 s100, 0xfffffd00
	s_mov_b32 s101, -1
	v_lshl_add_u64 v[120:121], v[120:121], 0, s[100:101]
	v_lshl_add_u64 v[122:123], v[122:123], 0, s[100:101]
	v_lshl_add_u64 v[124:125], v[124:125], 0, s[100:101]
	v_lshl_add_u64 v[126:127], v[126:127], 0, s[100:101]
	v_lshl_add_u64 v[128:129], v[128:129], 0, s[100:101]
	v_mfma_f32_32x32x16_bf16 v[80:95], v[164:167], v[156:159], v[80:95]
	v_mfma_f32_32x32x16_bf16 v[64:79], v[136:139], v[160:163], v[64:79]
	v_mfma_f32_32x32x16_bf16 v[48:63], v[140:143], v[160:163], v[48:63]
	v_mfma_f32_32x32x16_bf16 v[80:95], v[168:171], v[160:163], v[80:95]
	v_mfma_f32_32x32x16_bf16 v[32:47], v[144:147], v[160:163], v[32:47]
	v_mfma_f32_32x32x16_bf16 v[0:15], v[148:151], v[160:163], v[0:15]
	v_mfma_f32_32x32x16_bf16 v[16:31], v[152:155], v[160:163], v[16:31]
	ds_read_b128 v[120:123], v133 offset:12800
	ds_read_b128 v[124:127], v133 offset:15360
	ds_read_b128 v[136:139], v133 offset:17920
	ds_read_b128 v[140:143], v133 offset:20480
	ds_read_b128 v[144:147], v133 offset:23040
	ds_read_b128 v[148:151], v134
	ds_read_b128 v[152:155], v134 offset:32
	ds_read_b128 v[156:159], v133 offset:10240
	ds_read_b128 v[160:163], v133 offset:10272
	s_waitcnt lgkmcnt(3)
	v_mfma_f32_32x32x16_bf16 v[64:79], v[120:123], v[148:151], v[64:79]
	v_mfma_f32_32x32x16_bf16 v[48:63], v[124:127], v[148:151], v[48:63]
	s_waitcnt lgkmcnt(1)
	v_mfma_f32_32x32x16_bf16 v[80:95], v[156:159], v[148:151], v[80:95]
	v_mfma_f32_32x32x16_bf16 v[32:47], v[136:139], v[148:151], v[32:47]
	v_mfma_f32_32x32x16_bf16 v[0:15], v[140:143], v[148:151], v[0:15]
	v_mfma_f32_32x32x16_bf16 v[16:31], v[144:147], v[148:151], v[16:31]
	ds_read_b128 v[120:123], v133 offset:12832
	ds_read_b128 v[124:127], v133 offset:15392
	ds_read_b128 v[136:139], v133 offset:17952
	ds_read_b128 v[140:143], v133 offset:20512
	ds_read_b128 v[144:147], v133 offset:23072
	s_barrier
	s_waitcnt vmcnt(4)
	ds_write_b128 v130, v[96:99] offset:25600
	s_waitcnt vmcnt(3)
	ds_write_b128 v131, v[100:103] offset:25600
	s_waitcnt vmcnt(2)
	ds_write_b128 v130, v[104:107] offset:35840
	s_waitcnt vmcnt(1)
	ds_write_b128 v131, v[108:111] offset:35840
	s_waitcnt vmcnt(0)
	ds_write_b128 v132, v[112:115] offset:35840
	s_waitcnt lgkmcnt(0)
	s_barrier
	v_mfma_f32_32x32x16_bf16 v[64:79], v[120:123], v[152:155], v[64:79]
	v_mfma_f32_32x32x16_bf16 v[48:63], v[124:127], v[152:155], v[48:63]
	v_mfma_f32_32x32x16_bf16 v[80:95], v[160:163], v[152:155], v[80:95]
	v_mfma_f32_32x32x16_bf16 v[32:47], v[136:139], v[152:155], v[32:47]
	ds_read_b128 v[96:99], v133 offset:38400
	ds_read_b128 v[100:103], v133 offset:40960
	ds_read_b128 v[104:107], v133 offset:43520
	ds_read_b128 v[108:111], v133 offset:46080
	ds_read_b128 v[112:115], v133 offset:48640
	ds_read_b128 v[120:123], v134 offset:25600
	ds_read_b128 v[124:127], v134 offset:25632
	ds_read_b128 v[128:131], v133 offset:35840
	ds_read_b128 v[134:137], v133 offset:35872
	v_mfma_f32_32x32x16_bf16 v[0:15], v[140:143], v[152:155], v[0:15]
	v_mfma_f32_32x32x16_bf16 v[16:31], v[144:147], v[152:155], v[16:31]
	s_waitcnt lgkmcnt(3)
	v_mfma_f32_32x32x16_bf16 v[64:79], v[96:99], v[120:123], v[64:79]
	v_mfma_f32_32x32x16_bf16 v[48:63], v[100:103], v[120:123], v[48:63]
	s_waitcnt lgkmcnt(1)
	v_mfma_f32_32x32x16_bf16 v[80:95], v[128:131], v[120:123], v[80:95]
	v_mfma_f32_32x32x16_bf16 v[32:47], v[104:107], v[120:123], v[32:47]
	v_mfma_f32_32x32x16_bf16 v[0:15], v[108:111], v[120:123], v[0:15]
	v_mfma_f32_32x32x16_bf16 v[16:31], v[112:115], v[120:123], v[16:31]
	ds_read_b128 v[96:99], v133 offset:38432
	ds_read_b128 v[100:103], v133 offset:40992
	ds_read_b128 v[104:107], v133 offset:43552
	ds_read_b128 v[108:111], v133 offset:46112
	ds_read_b128 v[112:115], v133 offset:48672
	s_waitcnt lgkmcnt(0)
	s_barrier
	s_cmp_lg_u32 s10, 0
	s_cbranch_scc1 .Lq_stg_end
	s_barrier
